# pp tiles stored inside the output rows are written through (sc0 sc1) so no dirty line of them can later overwrite the output
# speedup vs baseline: 1.0043x; 1.0043x over previous
; __device__ __forceinline__ unsigned cvt_pk_bf16(float lo, float hi) { unsigned r; asm volatile("v_cvt_pk_bf16_f32 %0, %1, %2" : "=v"(r) : "v"(lo), "v"(hi)); return r; }
;     __device__ __forceinline__ void operator()(AccT& acc, const Unit& u, int wr, int wc, int fr, int fq) const {
;     ...
;         bf16_t* base = (u.L < 256 ? T0 : T1) + (size_t)(u.L & 255) * 65536 + (wr * 64 + fr) * 256 + wc * 32 + 8 * fq;
; #pragma unroll
;         for (int ai = 0; ai < 2; ++ai)
; #pragma unroll
;             for (int m = 0; m < 4; ++m) { bf16_t* rowp = base + (ai * 128 + m * 16) * 256;
; #pragma unroll
;                 for (int bj = 0; bj < 2; ++bj) { const f32x4 v0 = acc[ai][bj][m][0], v1 = acc[ai][bj][m][1];
;                     u32x4 w; w.x = cvt_pk_bf16(v0[0], v0[1]); w.y = cvt_pk_bf16(v0[2], v0[3]); w.z = cvt_pk_bf16(v1[0], v1[1]); w.w = cvt_pk_bf16(v1[2], v1[3]);
;                     *(u32x4*)(rowp + bj * 128) = w; } }
.LBB0_738:
	s_and_b32 s14, s78, 7
	s_lshl_b32 s14, s14, 6
	s_lshr_b32 s15, s78, 3
	s_add_i32 s14, s14, s15
	s_lshr_b32 s15, s14, 5
	s_lshl_b32 s15, s15, 3
	s_and_b32 s16, s14, 7
	s_add_i32 s15, s15, s16
	s_lshl_b32 s15, s15, 20
	s_bfe_u32 s16, s14, 0x20003
	s_lshl_b32 s16, s16, 17
	s_add_i32 s16, s16, s15
	s_cmpk_lt_i32 s78, 0x100
	v_mov_b32_e32 v144, v140
	s_cselect_b32 s15, s50, s53
	s_cselect_b32 s14, s51, s52
	v_mov_b32_e32 v146, v141
	s_add_u32 s14, s14, s16
	v_lshl_add_u32 v144, v144, 8, s72
	s_addc_u32 s15, s15, 0
	v_ashrrev_i32_e32 v145, 31, v144
	v_lshl_add_u64 v[144:145], v[144:145], 1, s[14:15]
	v_lshlrev_b32_e32 v146, 3, v146
	v_lshl_add_u64 v[144:145], v[144:145], 0, s[38:39]
	v_ashrrev_i32_e32 v147, 31, v146
	v_lshl_add_u64 v[144:145], v[146:147], 1, v[144:145]
	v_cvt_pk_bf16_f32 v122, v122, v123
	v_cvt_pk_bf16_f32 v123, v124, v125
	v_cvt_pk_bf16_f32 v124, v126, v127
	v_cvt_pk_bf16_f32 v125, v128, v129
	global_store_dwordx4 v[144:145], v[122:125], off sc0 sc1
	v_cvt_pk_bf16_f32 v118, v118, v119
	v_cvt_pk_bf16_f32 v119, v120, v121
	v_cvt_pk_bf16_f32 v120, v114, v115
	v_cvt_pk_bf16_f32 v121, v116, v117
	global_store_dwordx4 v[144:145], v[118:121], off offset:256 sc0 sc1
	v_cvt_pk_bf16_f32 v110, v110, v111
	v_cvt_pk_bf16_f32 v111, v112, v113
	v_cvt_pk_bf16_f32 v112, v106, v107
	v_add_co_u32_e32 v106, vcc, s83, v144
	s_movk_i32 s14, 0x4000
	s_nop 0
	v_addc_co_u32_e32 v107, vcc, 0, v145, vcc
	v_cvt_pk_bf16_f32 v113, v108, v109
	global_store_dwordx4 v[106:107], v[110:113], off sc0 sc1
	v_cvt_pk_bf16_f32 v102, v102, v103
	v_cvt_pk_bf16_f32 v103, v104, v105
	v_cvt_pk_bf16_f32 v104, v98, v99
	v_cvt_pk_bf16_f32 v105, v100, v101
	global_store_dwordx4 v[106:107], v[102:105], off offset:256 sc0 sc1
	v_cvt_pk_bf16_f32 v94, v94, v95
	v_cvt_pk_bf16_f32 v95, v96, v97
	v_cvt_pk_bf16_f32 v96, v90, v91
	v_add_co_u32_e32 v90, vcc, s14, v144
	s_movk_i32 s14, 0x6000
	s_nop 0
	v_addc_co_u32_e32 v91, vcc, 0, v145, vcc
	v_cvt_pk_bf16_f32 v97, v92, v93
	global_store_dwordx4 v[90:91], v[94:97], off sc0 sc1
	v_cvt_pk_bf16_f32 v86, v86, v87
	v_cvt_pk_bf16_f32 v87, v88, v89
	v_cvt_pk_bf16_f32 v88, v82, v83
	v_cvt_pk_bf16_f32 v89, v84, v85
	global_store_dwordx4 v[90:91], v[86:89], off offset:256 sc0 sc1
	v_cvt_pk_bf16_f32 v78, v78, v79
	v_cvt_pk_bf16_f32 v79, v80, v81
	v_cvt_pk_bf16_f32 v80, v74, v75
	v_add_co_u32_e32 v74, vcc, s14, v144
	v_cvt_pk_bf16_f32 v81, v76, v77
	s_mov_b32 s14, 0x12000
	s_nop 0
	v_addc_co_u32_e32 v75, vcc, 0, v145, vcc
	global_store_dwordx4 v[74:75], v[78:81], off sc0 sc1
	v_cvt_pk_bf16_f32 v70, v70, v71
	v_cvt_pk_bf16_f32 v71, v72, v73
	v_cvt_pk_bf16_f32 v72, v66, v67
	v_cvt_pk_bf16_f32 v73, v68, v69
	global_store_dwordx4 v[74:75], v[70:73], off offset:256 sc0 sc1
	v_cvt_pk_bf16_f32 v62, v62, v63
	v_cvt_pk_bf16_f32 v63, v64, v65
	v_cvt_pk_bf16_f32 v64, v58, v59
	v_add_co_u32_e32 v58, vcc, s56, v144
	v_cvt_pk_bf16_f32 v65, v60, v61
	s_mov_b32 s78, s77
	s_nop 0
	v_addc_co_u32_e32 v59, vcc, 0, v145, vcc
	global_store_dwordx4 v[58:59], v[62:65], off sc0 sc1
	v_cvt_pk_bf16_f32 v54, v54, v55
	v_cvt_pk_bf16_f32 v55, v56, v57
	v_cvt_pk_bf16_f32 v56, v50, v51
	v_cvt_pk_bf16_f32 v57, v52, v53
	global_store_dwordx4 v[58:59], v[54:57], off offset:256 sc0 sc1
	v_cvt_pk_bf16_f32 v46, v46, v47
	v_cvt_pk_bf16_f32 v47, v48, v49
	v_cvt_pk_bf16_f32 v48, v42, v43
	v_add_co_u32_e32 v42, vcc, s14, v144
	s_mov_b32 s14, 0x14000
	s_nop 0
	v_addc_co_u32_e32 v43, vcc, 0, v145, vcc
	v_cvt_pk_bf16_f32 v49, v44, v45
	global_store_dwordx4 v[42:43], v[46:49], off sc0 sc1
	v_cvt_pk_bf16_f32 v38, v38, v39
	v_cvt_pk_bf16_f32 v39, v40, v41
	v_cvt_pk_bf16_f32 v40, v34, v35
	v_cvt_pk_bf16_f32 v41, v36, v37
	global_store_dwordx4 v[42:43], v[38:41], off offset:256 sc0 sc1
	v_cvt_pk_bf16_f32 v30, v30, v31
	v_cvt_pk_bf16_f32 v31, v32, v33
	v_cvt_pk_bf16_f32 v32, v26, v27
	v_add_co_u32_e32 v26, vcc, s14, v144
	v_cvt_pk_bf16_f32 v33, v28, v29
	s_mov_b64 s[16:17], s[12:13]
	s_nop 0
	v_addc_co_u32_e32 v27, vcc, 0, v145, vcc
	global_store_dwordx4 v[26:27], v[30:33], off sc0 sc1
	v_cvt_pk_bf16_f32 v22, v22, v23
	v_cvt_pk_bf16_f32 v23, v24, v25
	v_cvt_pk_bf16_f32 v24, v18, v19
	v_cvt_pk_bf16_f32 v25, v20, v21
	global_store_dwordx4 v[26:27], v[22:25], off offset:256 sc0 sc1
	v_cvt_pk_bf16_f32 v14, v14, v15
	v_cvt_pk_bf16_f32 v15, v16, v17
	v_cvt_pk_bf16_f32 v16, v10, v11
	v_add_co_u32_e32 v10, vcc, 0x16000, v144
	s_mov_b64 s[14:15], s[10:11]
	s_nop 0
	v_addc_co_u32_e32 v11, vcc, 0, v145, vcc
	s_and_b64 vcc, exec, s[40:41]
	v_cvt_pk_bf16_f32 v17, v12, v13
	global_store_dwordx4 v[10:11], v[14:17], off sc0 sc1
	v_cvt_pk_bf16_f32 v6, v6, v7
	v_cvt_pk_bf16_f32 v7, v8, v9
	v_cvt_pk_bf16_f32 v8, v2, v3
	v_cvt_pk_bf16_f32 v9, v4, v5
	global_store_dwordx4 v[10:11], v[6:9], off offset:256 sc0 sc1
	s_cbranch_vccnz .LBB0_753
